# phase_shw rewritten: weight rows requested 16 ahead instead of one per dependent step
# speedup vs baseline: 1.0177x; 1.0079x over previous
.Lp1_done:
.LBB0_1059:
	s_or_b64 exec, exec, s[2:3]
	v_mov_b32_e32 v0, v163
	v_mov_b32_e32 v1, v163
	v_readlane_b32 s0, v250, 7
	v_ashrrev_i32_e32 v2, 6, v1
	s_nop 0
	v_add_u32_e32 v46, s0, v2
	s_movk_i32 s0, 0x580
	v_cmp_gt_i32_e32 vcc, s0, v46
	s_and_saveexec_b64 s[0:1], vcc
	v_readlane_b32 s36, v251, 28
	v_readlane_b32 s37, v251, 29
	s_cbranch_execz .LBB0_1070
	v_readlane_b32 s4, v249, 14
	v_readlane_b32 s5, v249, 15
	v_readlane_b32 s6, v254, 36
	v_readlane_b32 s7, v254, 37
	v_readlane_b32 s8, v251, 6
	v_readlane_b32 s9, v251, 7
	v_readlane_b32 s12, v250, 7
	v_readlane_b32 s13, v255, 4
	v_lshrrev_b32_e32 v144, 6, v163
	v_and_b32_e32 v146, 63, v163
	v_readfirstlane_b32 s26, v144
	v_lshlrev_b32_e32 v146, 4, v146
	s_add_u32 s12, s12, s26
.Lshw_item:
	s_and_b32 s2, s12, 31
	s_lshr_b32 s3, s12, 5
	s_cmp_lt_u32 s3, 16
	s_cbranch_scc0 .Lshw_g1
	s_mov_b64 s[14:15], s[6:7]
	s_add_u32 s16, s4, 0x3000
	s_addc_u32 s17, s5, 0
	s_mov_b32 s26, 0x1D800000
	s_mov_b32 s27, 0x4000
	s_branch .Lshw_sel
.Lshw_g1:
	s_cmp_lt_u32 s3, 28
	s_cbranch_scc0 .Lshw_g2
	s_sub_u32 s3, s3, 16
	s_mov_b64 s[14:15], s[8:9]
	s_add_u32 s16, s4, 0x1E000
	s_addc_u32 s17, s5, 0
	s_mov_b32 s26, 0x1D810000
	s_mov_b32 s27, 0x3000
	s_branch .Lshw_sel
.Lshw_g2:
	s_sub_u32 s3, s3, 28
	s_add_u32 s14, s6, 0x1000000
	s_addc_u32 s15, s7, 0
	s_add_u32 s16, s4, 0x21000
	s_addc_u32 s17, s5, 0
	s_mov_b32 s26, 0x1D81C000
	s_mov_b32 s27, 0x4000
.Lshw_sel:
	s_mul_i32 s24, s2, 0x2C000
	s_add_u32 s26, s26, s24
	s_add_u32 s24, s4, s26
	s_addc_u32 s25, s5, 0
	s_lshl_b32 s26, s2, 7
	s_add_u32 s16, s16, s26
	s_addc_u32 s17, s17, 0
	s_add_u32 s18, s16, 0x6000
	s_addc_u32 s19, s17, 0
	s_add_u32 s20, s18, 0x6000
	s_addc_u32 s21, s19, 0
	s_add_u32 s22, s20, 0x6000
	s_addc_u32 s23, s21, 0
	s_lshl_b32 s26, s2, 5
	s_mul_i32 s26, s26, s27
	s_add_u32 s14, s14, s26
	s_addc_u32 s15, s15, 0
	s_lshl_b32 s26, s3, 10
	v_add_u32_e32 v145, s26, v146
	v_mov_b32_e32 v144, v145
	global_load_dwordx4 v[0:3], v161, s[16:17] offset:0
	global_load_dwordx4 v[4:7], v161, s[16:17] offset:16
	global_load_dwordx4 v[8:11], v161, s[16:17] offset:32
	global_load_dwordx4 v[12:15], v161, s[16:17] offset:48
	global_load_dwordx4 v[16:19], v161, s[16:17] offset:64
	global_load_dwordx4 v[20:23], v161, s[16:17] offset:80
	global_load_dwordx4 v[24:27], v161, s[16:17] offset:96
	global_load_dwordx4 v[28:31], v161, s[16:17] offset:112
	global_load_dwordx4 v[32:35], v161, s[18:19] offset:0
	global_load_dwordx4 v[36:39], v161, s[18:19] offset:16
	global_load_dwordx4 v[40:43], v161, s[18:19] offset:32
	global_load_dwordx4 v[44:47], v161, s[18:19] offset:48
	global_load_dwordx4 v[48:51], v161, s[18:19] offset:64
	global_load_dwordx4 v[52:55], v161, s[18:19] offset:80
	global_load_dwordx4 v[56:59], v161, s[18:19] offset:96
	global_load_dwordx4 v[60:63], v161, s[18:19] offset:112
	global_load_dwordx4 v[64:67], v161, s[20:21] offset:0
	global_load_dwordx4 v[68:71], v161, s[20:21] offset:16
	global_load_dwordx4 v[72:75], v161, s[20:21] offset:32
	global_load_dwordx4 v[76:79], v161, s[20:21] offset:48
	global_load_dwordx4 v[80:83], v161, s[20:21] offset:64
	global_load_dwordx4 v[84:87], v161, s[20:21] offset:80
	global_load_dwordx4 v[88:91], v161, s[20:21] offset:96
	global_load_dwordx4 v[92:95], v161, s[20:21] offset:112
	global_load_dwordx4 v[96:99], v161, s[22:23] offset:0
	global_load_dwordx4 v[100:103], v161, s[22:23] offset:16
	global_load_dwordx4 v[104:107], v161, s[22:23] offset:32
	global_load_dwordx4 v[108:111], v161, s[22:23] offset:48
	global_load_dwordx4 v[112:115], v161, s[22:23] offset:64
	global_load_dwordx4 v[116:119], v161, s[22:23] offset:80
	global_load_dwordx4 v[120:123], v161, s[22:23] offset:96
	global_load_dwordx4 v[124:127], v161, s[22:23] offset:112
	global_load_dwordx4 v[164:167], v144, s[14:15]
	v_add_u32_e32 v144, s27, v144
	global_load_dwordx4 v[168:171], v144, s[14:15]
	v_add_u32_e32 v144, s27, v144
	global_load_dwordx4 v[172:175], v144, s[14:15]
	v_add_u32_e32 v144, s27, v144
	global_load_dwordx4 v[176:179], v144, s[14:15]
	v_add_u32_e32 v144, s27, v144
	global_load_dwordx4 v[180:183], v144, s[14:15]
	v_add_u32_e32 v144, s27, v144
	global_load_dwordx4 v[184:187], v144, s[14:15]
	v_add_u32_e32 v144, s27, v144
	global_load_dwordx4 v[188:191], v144, s[14:15]
	v_add_u32_e32 v144, s27, v144
	global_load_dwordx4 v[192:195], v144, s[14:15]
	v_add_u32_e32 v144, s27, v144
	global_load_dwordx4 v[196:199], v144, s[14:15]
	v_add_u32_e32 v144, s27, v144
	global_load_dwordx4 v[200:203], v144, s[14:15]
	v_add_u32_e32 v144, s27, v144
	global_load_dwordx4 v[204:207], v144, s[14:15]
	v_add_u32_e32 v144, s27, v144
	global_load_dwordx4 v[208:211], v144, s[14:15]
	v_add_u32_e32 v144, s27, v144
	global_load_dwordx4 v[212:215], v144, s[14:15]
	v_add_u32_e32 v144, s27, v144
	global_load_dwordx4 v[216:219], v144, s[14:15]
	v_add_u32_e32 v144, s27, v144
	global_load_dwordx4 v[220:223], v144, s[14:15]
	v_add_u32_e32 v144, s27, v144
	global_load_dwordx4 v[224:227], v144, s[14:15]
	v_add_u32_e32 v144, s27, v144
	v_mov_b32_e32 v128, 0
	v_mov_b32_e32 v129, 0
	v_mov_b32_e32 v130, 0
	v_mov_b32_e32 v131, 0
	v_mov_b32_e32 v132, 0
	v_mov_b32_e32 v133, 0
	v_mov_b32_e32 v134, 0
	v_mov_b32_e32 v135, 0
	v_mov_b32_e32 v136, 0
	v_mov_b32_e32 v137, 0
	v_mov_b32_e32 v138, 0
	v_mov_b32_e32 v139, 0
	v_mov_b32_e32 v140, 0
	v_mov_b32_e32 v141, 0
	v_mov_b32_e32 v142, 0
	v_mov_b32_e32 v143, 0
	s_waitcnt vmcnt(15)
	v_pk_fma_f32 v[128:129], v[164:165], v[0:1], v[128:129] op_sel_hi:[1,0,1]
	v_pk_fma_f32 v[130:131], v[166:167], v[0:1], v[130:131] op_sel_hi:[1,0,1]
	v_pk_fma_f32 v[132:133], v[164:165], v[32:33], v[132:133] op_sel_hi:[1,0,1]
	v_pk_fma_f32 v[134:135], v[166:167], v[32:33], v[134:135] op_sel_hi:[1,0,1]
	v_pk_fma_f32 v[136:137], v[164:165], v[64:65], v[136:137] op_sel_hi:[1,0,1]
	v_pk_fma_f32 v[138:139], v[166:167], v[64:65], v[138:139] op_sel_hi:[1,0,1]
	v_pk_fma_f32 v[140:141], v[164:165], v[96:97], v[140:141] op_sel_hi:[1,0,1]
	v_pk_fma_f32 v[142:143], v[166:167], v[96:97], v[142:143] op_sel_hi:[1,0,1]
	global_load_dwordx4 v[164:167], v144, s[14:15]
	v_add_u32_e32 v144, s27, v144
	s_waitcnt vmcnt(15)
	v_pk_fma_f32 v[128:129], v[168:169], v[0:1], v[128:129] op_sel:[0,1,0]
	v_pk_fma_f32 v[130:131], v[170:171], v[0:1], v[130:131] op_sel:[0,1,0]
	v_pk_fma_f32 v[132:133], v[168:169], v[32:33], v[132:133] op_sel:[0,1,0]
	v_pk_fma_f32 v[134:135], v[170:171], v[32:33], v[134:135] op_sel:[0,1,0]
	v_pk_fma_f32 v[136:137], v[168:169], v[64:65], v[136:137] op_sel:[0,1,0]
	v_pk_fma_f32 v[138:139], v[170:171], v[64:65], v[138:139] op_sel:[0,1,0]
	v_pk_fma_f32 v[140:141], v[168:169], v[96:97], v[140:141] op_sel:[0,1,0]
	v_pk_fma_f32 v[142:143], v[170:171], v[96:97], v[142:143] op_sel:[0,1,0]
	global_load_dwordx4 v[168:171], v144, s[14:15]
	v_add_u32_e32 v144, s27, v144
	s_waitcnt vmcnt(15)
	v_pk_fma_f32 v[128:129], v[172:173], v[2:3], v[128:129] op_sel_hi:[1,0,1]
	v_pk_fma_f32 v[130:131], v[174:175], v[2:3], v[130:131] op_sel_hi:[1,0,1]
	v_pk_fma_f32 v[132:133], v[172:173], v[34:35], v[132:133] op_sel_hi:[1,0,1]
	v_pk_fma_f32 v[134:135], v[174:175], v[34:35], v[134:135] op_sel_hi:[1,0,1]
	v_pk_fma_f32 v[136:137], v[172:173], v[66:67], v[136:137] op_sel_hi:[1,0,1]
	v_pk_fma_f32 v[138:139], v[174:175], v[66:67], v[138:139] op_sel_hi:[1,0,1]
	v_pk_fma_f32 v[140:141], v[172:173], v[98:99], v[140:141] op_sel_hi:[1,0,1]
	v_pk_fma_f32 v[142:143], v[174:175], v[98:99], v[142:143] op_sel_hi:[1,0,1]
	global_load_dwordx4 v[172:175], v144, s[14:15]
	v_add_u32_e32 v144, s27, v144
	s_waitcnt vmcnt(15)
	v_pk_fma_f32 v[128:129], v[176:177], v[2:3], v[128:129] op_sel:[0,1,0]
	v_pk_fma_f32 v[130:131], v[178:179], v[2:3], v[130:131] op_sel:[0,1,0]
	v_pk_fma_f32 v[132:133], v[176:177], v[34:35], v[132:133] op_sel:[0,1,0]
	v_pk_fma_f32 v[134:135], v[178:179], v[34:35], v[134:135] op_sel:[0,1,0]
	v_pk_fma_f32 v[136:137], v[176:177], v[66:67], v[136:137] op_sel:[0,1,0]
	v_pk_fma_f32 v[138:139], v[178:179], v[66:67], v[138:139] op_sel:[0,1,0]
	v_pk_fma_f32 v[140:141], v[176:177], v[98:99], v[140:141] op_sel:[0,1,0]
	v_pk_fma_f32 v[142:143], v[178:179], v[98:99], v[142:143] op_sel:[0,1,0]
	global_load_dwordx4 v[176:179], v144, s[14:15]
	v_add_u32_e32 v144, s27, v144
	s_waitcnt vmcnt(15)
	v_pk_fma_f32 v[128:129], v[180:181], v[4:5], v[128:129] op_sel_hi:[1,0,1]
	v_pk_fma_f32 v[130:131], v[182:183], v[4:5], v[130:131] op_sel_hi:[1,0,1]
	v_pk_fma_f32 v[132:133], v[180:181], v[36:37], v[132:133] op_sel_hi:[1,0,1]
	v_pk_fma_f32 v[134:135], v[182:183], v[36:37], v[134:135] op_sel_hi:[1,0,1]
	v_pk_fma_f32 v[136:137], v[180:181], v[68:69], v[136:137] op_sel_hi:[1,0,1]
	v_pk_fma_f32 v[138:139], v[182:183], v[68:69], v[138:139] op_sel_hi:[1,0,1]
	v_pk_fma_f32 v[140:141], v[180:181], v[100:101], v[140:141] op_sel_hi:[1,0,1]
	v_pk_fma_f32 v[142:143], v[182:183], v[100:101], v[142:143] op_sel_hi:[1,0,1]
	global_load_dwordx4 v[180:183], v144, s[14:15]
	v_add_u32_e32 v144, s27, v144
	s_waitcnt vmcnt(15)
	v_pk_fma_f32 v[128:129], v[184:185], v[4:5], v[128:129] op_sel:[0,1,0]
	v_pk_fma_f32 v[130:131], v[186:187], v[4:5], v[130:131] op_sel:[0,1,0]
	v_pk_fma_f32 v[132:133], v[184:185], v[36:37], v[132:133] op_sel:[0,1,0]
	v_pk_fma_f32 v[134:135], v[186:187], v[36:37], v[134:135] op_sel:[0,1,0]
	v_pk_fma_f32 v[136:137], v[184:185], v[68:69], v[136:137] op_sel:[0,1,0]
	v_pk_fma_f32 v[138:139], v[186:187], v[68:69], v[138:139] op_sel:[0,1,0]
	v_pk_fma_f32 v[140:141], v[184:185], v[100:101], v[140:141] op_sel:[0,1,0]
	v_pk_fma_f32 v[142:143], v[186:187], v[100:101], v[142:143] op_sel:[0,1,0]
	global_load_dwordx4 v[184:187], v144, s[14:15]
	v_add_u32_e32 v144, s27, v144
	s_waitcnt vmcnt(15)
	v_pk_fma_f32 v[128:129], v[188:189], v[6:7], v[128:129] op_sel_hi:[1,0,1]
	v_pk_fma_f32 v[130:131], v[190:191], v[6:7], v[130:131] op_sel_hi:[1,0,1]
	v_pk_fma_f32 v[132:133], v[188:189], v[38:39], v[132:133] op_sel_hi:[1,0,1]
	v_pk_fma_f32 v[134:135], v[190:191], v[38:39], v[134:135] op_sel_hi:[1,0,1]
	v_pk_fma_f32 v[136:137], v[188:189], v[70:71], v[136:137] op_sel_hi:[1,0,1]
	v_pk_fma_f32 v[138:139], v[190:191], v[70:71], v[138:139] op_sel_hi:[1,0,1]
	v_pk_fma_f32 v[140:141], v[188:189], v[102:103], v[140:141] op_sel_hi:[1,0,1]
	v_pk_fma_f32 v[142:143], v[190:191], v[102:103], v[142:143] op_sel_hi:[1,0,1]
	global_load_dwordx4 v[188:191], v144, s[14:15]
	v_add_u32_e32 v144, s27, v144
	s_waitcnt vmcnt(15)
	v_pk_fma_f32 v[128:129], v[192:193], v[6:7], v[128:129] op_sel:[0,1,0]
	v_pk_fma_f32 v[130:131], v[194:195], v[6:7], v[130:131] op_sel:[0,1,0]
	v_pk_fma_f32 v[132:133], v[192:193], v[38:39], v[132:133] op_sel:[0,1,0]
	v_pk_fma_f32 v[134:135], v[194:195], v[38:39], v[134:135] op_sel:[0,1,0]
	v_pk_fma_f32 v[136:137], v[192:193], v[70:71], v[136:137] op_sel:[0,1,0]
	v_pk_fma_f32 v[138:139], v[194:195], v[70:71], v[138:139] op_sel:[0,1,0]
	v_pk_fma_f32 v[140:141], v[192:193], v[102:103], v[140:141] op_sel:[0,1,0]
	v_pk_fma_f32 v[142:143], v[194:195], v[102:103], v[142:143] op_sel:[0,1,0]
	global_load_dwordx4 v[192:195], v144, s[14:15]
	v_add_u32_e32 v144, s27, v144
	s_waitcnt vmcnt(15)
	v_pk_fma_f32 v[128:129], v[196:197], v[8:9], v[128:129] op_sel_hi:[1,0,1]
	v_pk_fma_f32 v[130:131], v[198:199], v[8:9], v[130:131] op_sel_hi:[1,0,1]
	v_pk_fma_f32 v[132:133], v[196:197], v[40:41], v[132:133] op_sel_hi:[1,0,1]
	v_pk_fma_f32 v[134:135], v[198:199], v[40:41], v[134:135] op_sel_hi:[1,0,1]
	v_pk_fma_f32 v[136:137], v[196:197], v[72:73], v[136:137] op_sel_hi:[1,0,1]
	v_pk_fma_f32 v[138:139], v[198:199], v[72:73], v[138:139] op_sel_hi:[1,0,1]
	v_pk_fma_f32 v[140:141], v[196:197], v[104:105], v[140:141] op_sel_hi:[1,0,1]
	v_pk_fma_f32 v[142:143], v[198:199], v[104:105], v[142:143] op_sel_hi:[1,0,1]
	global_load_dwordx4 v[196:199], v144, s[14:15]
	v_add_u32_e32 v144, s27, v144
	s_waitcnt vmcnt(15)
	v_pk_fma_f32 v[128:129], v[200:201], v[8:9], v[128:129] op_sel:[0,1,0]
	v_pk_fma_f32 v[130:131], v[202:203], v[8:9], v[130:131] op_sel:[0,1,0]
	v_pk_fma_f32 v[132:133], v[200:201], v[40:41], v[132:133] op_sel:[0,1,0]
	v_pk_fma_f32 v[134:135], v[202:203], v[40:41], v[134:135] op_sel:[0,1,0]
	v_pk_fma_f32 v[136:137], v[200:201], v[72:73], v[136:137] op_sel:[0,1,0]
	v_pk_fma_f32 v[138:139], v[202:203], v[72:73], v[138:139] op_sel:[0,1,0]
	v_pk_fma_f32 v[140:141], v[200:201], v[104:105], v[140:141] op_sel:[0,1,0]
	v_pk_fma_f32 v[142:143], v[202:203], v[104:105], v[142:143] op_sel:[0,1,0]
	global_load_dwordx4 v[200:203], v144, s[14:15]
	v_add_u32_e32 v144, s27, v144
	s_waitcnt vmcnt(15)
	v_pk_fma_f32 v[128:129], v[204:205], v[10:11], v[128:129] op_sel_hi:[1,0,1]
	v_pk_fma_f32 v[130:131], v[206:207], v[10:11], v[130:131] op_sel_hi:[1,0,1]
	v_pk_fma_f32 v[132:133], v[204:205], v[42:43], v[132:133] op_sel_hi:[1,0,1]
	v_pk_fma_f32 v[134:135], v[206:207], v[42:43], v[134:135] op_sel_hi:[1,0,1]
	v_pk_fma_f32 v[136:137], v[204:205], v[74:75], v[136:137] op_sel_hi:[1,0,1]
	v_pk_fma_f32 v[138:139], v[206:207], v[74:75], v[138:139] op_sel_hi:[1,0,1]
	v_pk_fma_f32 v[140:141], v[204:205], v[106:107], v[140:141] op_sel_hi:[1,0,1]
	v_pk_fma_f32 v[142:143], v[206:207], v[106:107], v[142:143] op_sel_hi:[1,0,1]
	global_load_dwordx4 v[204:207], v144, s[14:15]
	v_add_u32_e32 v144, s27, v144
	s_waitcnt vmcnt(15)
	v_pk_fma_f32 v[128:129], v[208:209], v[10:11], v[128:129] op_sel:[0,1,0]
	v_pk_fma_f32 v[130:131], v[210:211], v[10:11], v[130:131] op_sel:[0,1,0]
	v_pk_fma_f32 v[132:133], v[208:209], v[42:43], v[132:133] op_sel:[0,1,0]
	v_pk_fma_f32 v[134:135], v[210:211], v[42:43], v[134:135] op_sel:[0,1,0]
	v_pk_fma_f32 v[136:137], v[208:209], v[74:75], v[136:137] op_sel:[0,1,0]
	v_pk_fma_f32 v[138:139], v[210:211], v[74:75], v[138:139] op_sel:[0,1,0]
	v_pk_fma_f32 v[140:141], v[208:209], v[106:107], v[140:141] op_sel:[0,1,0]
	v_pk_fma_f32 v[142:143], v[210:211], v[106:107], v[142:143] op_sel:[0,1,0]
	global_load_dwordx4 v[208:211], v144, s[14:15]
	v_add_u32_e32 v144, s27, v144
	s_waitcnt vmcnt(15)
	v_pk_fma_f32 v[128:129], v[212:213], v[12:13], v[128:129] op_sel_hi:[1,0,1]
	v_pk_fma_f32 v[130:131], v[214:215], v[12:13], v[130:131] op_sel_hi:[1,0,1]
	v_pk_fma_f32 v[132:133], v[212:213], v[44:45], v[132:133] op_sel_hi:[1,0,1]
	v_pk_fma_f32 v[134:135], v[214:215], v[44:45], v[134:135] op_sel_hi:[1,0,1]
	v_pk_fma_f32 v[136:137], v[212:213], v[76:77], v[136:137] op_sel_hi:[1,0,1]
	v_pk_fma_f32 v[138:139], v[214:215], v[76:77], v[138:139] op_sel_hi:[1,0,1]
	v_pk_fma_f32 v[140:141], v[212:213], v[108:109], v[140:141] op_sel_hi:[1,0,1]
	v_pk_fma_f32 v[142:143], v[214:215], v[108:109], v[142:143] op_sel_hi:[1,0,1]
	global_load_dwordx4 v[212:215], v144, s[14:15]
	v_add_u32_e32 v144, s27, v144
	s_waitcnt vmcnt(15)
	v_pk_fma_f32 v[128:129], v[216:217], v[12:13], v[128:129] op_sel:[0,1,0]
	v_pk_fma_f32 v[130:131], v[218:219], v[12:13], v[130:131] op_sel:[0,1,0]
	v_pk_fma_f32 v[132:133], v[216:217], v[44:45], v[132:133] op_sel:[0,1,0]
	v_pk_fma_f32 v[134:135], v[218:219], v[44:45], v[134:135] op_sel:[0,1,0]
	v_pk_fma_f32 v[136:137], v[216:217], v[76:77], v[136:137] op_sel:[0,1,0]
	v_pk_fma_f32 v[138:139], v[218:219], v[76:77], v[138:139] op_sel:[0,1,0]
	v_pk_fma_f32 v[140:141], v[216:217], v[108:109], v[140:141] op_sel:[0,1,0]
	v_pk_fma_f32 v[142:143], v[218:219], v[108:109], v[142:143] op_sel:[0,1,0]
	global_load_dwordx4 v[216:219], v144, s[14:15]
	v_add_u32_e32 v144, s27, v144
	s_waitcnt vmcnt(15)
	v_pk_fma_f32 v[128:129], v[220:221], v[14:15], v[128:129] op_sel_hi:[1,0,1]
	v_pk_fma_f32 v[130:131], v[222:223], v[14:15], v[130:131] op_sel_hi:[1,0,1]
	v_pk_fma_f32 v[132:133], v[220:221], v[46:47], v[132:133] op_sel_hi:[1,0,1]
	v_pk_fma_f32 v[134:135], v[222:223], v[46:47], v[134:135] op_sel_hi:[1,0,1]
	v_pk_fma_f32 v[136:137], v[220:221], v[78:79], v[136:137] op_sel_hi:[1,0,1]
	v_pk_fma_f32 v[138:139], v[222:223], v[78:79], v[138:139] op_sel_hi:[1,0,1]
	v_pk_fma_f32 v[140:141], v[220:221], v[110:111], v[140:141] op_sel_hi:[1,0,1]
	v_pk_fma_f32 v[142:143], v[222:223], v[110:111], v[142:143] op_sel_hi:[1,0,1]
	global_load_dwordx4 v[220:223], v144, s[14:15]
	v_add_u32_e32 v144, s27, v144
	s_waitcnt vmcnt(15)
	v_pk_fma_f32 v[128:129], v[224:225], v[14:15], v[128:129] op_sel:[0,1,0]
	v_pk_fma_f32 v[130:131], v[226:227], v[14:15], v[130:131] op_sel:[0,1,0]
	v_pk_fma_f32 v[132:133], v[224:225], v[46:47], v[132:133] op_sel:[0,1,0]
	v_pk_fma_f32 v[134:135], v[226:227], v[46:47], v[134:135] op_sel:[0,1,0]
	v_pk_fma_f32 v[136:137], v[224:225], v[78:79], v[136:137] op_sel:[0,1,0]
	v_pk_fma_f32 v[138:139], v[226:227], v[78:79], v[138:139] op_sel:[0,1,0]
	v_pk_fma_f32 v[140:141], v[224:225], v[110:111], v[140:141] op_sel:[0,1,0]
	v_pk_fma_f32 v[142:143], v[226:227], v[110:111], v[142:143] op_sel:[0,1,0]
	global_load_dwordx4 v[224:227], v144, s[14:15]
	v_add_u32_e32 v144, s27, v144
	s_waitcnt vmcnt(15)
	v_pk_fma_f32 v[128:129], v[164:165], v[16:17], v[128:129] op_sel_hi:[1,0,1]
	v_pk_fma_f32 v[130:131], v[166:167], v[16:17], v[130:131] op_sel_hi:[1,0,1]
	v_pk_fma_f32 v[132:133], v[164:165], v[48:49], v[132:133] op_sel_hi:[1,0,1]
	v_pk_fma_f32 v[134:135], v[166:167], v[48:49], v[134:135] op_sel_hi:[1,0,1]
	v_pk_fma_f32 v[136:137], v[164:165], v[80:81], v[136:137] op_sel_hi:[1,0,1]
	v_pk_fma_f32 v[138:139], v[166:167], v[80:81], v[138:139] op_sel_hi:[1,0,1]
	v_pk_fma_f32 v[140:141], v[164:165], v[112:113], v[140:141] op_sel_hi:[1,0,1]
	v_pk_fma_f32 v[142:143], v[166:167], v[112:113], v[142:143] op_sel_hi:[1,0,1]
	s_waitcnt vmcnt(14)
	v_pk_fma_f32 v[128:129], v[168:169], v[16:17], v[128:129] op_sel:[0,1,0]
	v_pk_fma_f32 v[130:131], v[170:171], v[16:17], v[130:131] op_sel:[0,1,0]
	v_pk_fma_f32 v[132:133], v[168:169], v[48:49], v[132:133] op_sel:[0,1,0]
	v_pk_fma_f32 v[134:135], v[170:171], v[48:49], v[134:135] op_sel:[0,1,0]
	v_pk_fma_f32 v[136:137], v[168:169], v[80:81], v[136:137] op_sel:[0,1,0]
	v_pk_fma_f32 v[138:139], v[170:171], v[80:81], v[138:139] op_sel:[0,1,0]
	v_pk_fma_f32 v[140:141], v[168:169], v[112:113], v[140:141] op_sel:[0,1,0]
	v_pk_fma_f32 v[142:143], v[170:171], v[112:113], v[142:143] op_sel:[0,1,0]
	s_waitcnt vmcnt(13)
	v_pk_fma_f32 v[128:129], v[172:173], v[18:19], v[128:129] op_sel_hi:[1,0,1]
	v_pk_fma_f32 v[130:131], v[174:175], v[18:19], v[130:131] op_sel_hi:[1,0,1]
	v_pk_fma_f32 v[132:133], v[172:173], v[50:51], v[132:133] op_sel_hi:[1,0,1]
	v_pk_fma_f32 v[134:135], v[174:175], v[50:51], v[134:135] op_sel_hi:[1,0,1]
	v_pk_fma_f32 v[136:137], v[172:173], v[82:83], v[136:137] op_sel_hi:[1,0,1]
	v_pk_fma_f32 v[138:139], v[174:175], v[82:83], v[138:139] op_sel_hi:[1,0,1]
	v_pk_fma_f32 v[140:141], v[172:173], v[114:115], v[140:141] op_sel_hi:[1,0,1]
	v_pk_fma_f32 v[142:143], v[174:175], v[114:115], v[142:143] op_sel_hi:[1,0,1]
	s_waitcnt vmcnt(12)
	v_pk_fma_f32 v[128:129], v[176:177], v[18:19], v[128:129] op_sel:[0,1,0]
	v_pk_fma_f32 v[130:131], v[178:179], v[18:19], v[130:131] op_sel:[0,1,0]
	v_pk_fma_f32 v[132:133], v[176:177], v[50:51], v[132:133] op_sel:[0,1,0]
	v_pk_fma_f32 v[134:135], v[178:179], v[50:51], v[134:135] op_sel:[0,1,0]
	v_pk_fma_f32 v[136:137], v[176:177], v[82:83], v[136:137] op_sel:[0,1,0]
	v_pk_fma_f32 v[138:139], v[178:179], v[82:83], v[138:139] op_sel:[0,1,0]
	v_pk_fma_f32 v[140:141], v[176:177], v[114:115], v[140:141] op_sel:[0,1,0]
	v_pk_fma_f32 v[142:143], v[178:179], v[114:115], v[142:143] op_sel:[0,1,0]
	s_waitcnt vmcnt(11)
	v_pk_fma_f32 v[128:129], v[180:181], v[20:21], v[128:129] op_sel_hi:[1,0,1]
	v_pk_fma_f32 v[130:131], v[182:183], v[20:21], v[130:131] op_sel_hi:[1,0,1]
	v_pk_fma_f32 v[132:133], v[180:181], v[52:53], v[132:133] op_sel_hi:[1,0,1]
	v_pk_fma_f32 v[134:135], v[182:183], v[52:53], v[134:135] op_sel_hi:[1,0,1]
	v_pk_fma_f32 v[136:137], v[180:181], v[84:85], v[136:137] op_sel_hi:[1,0,1]
	v_pk_fma_f32 v[138:139], v[182:183], v[84:85], v[138:139] op_sel_hi:[1,0,1]
	v_pk_fma_f32 v[140:141], v[180:181], v[116:117], v[140:141] op_sel_hi:[1,0,1]
	v_pk_fma_f32 v[142:143], v[182:183], v[116:117], v[142:143] op_sel_hi:[1,0,1]
	s_waitcnt vmcnt(10)
	v_pk_fma_f32 v[128:129], v[184:185], v[20:21], v[128:129] op_sel:[0,1,0]
	v_pk_fma_f32 v[130:131], v[186:187], v[20:21], v[130:131] op_sel:[0,1,0]
	v_pk_fma_f32 v[132:133], v[184:185], v[52:53], v[132:133] op_sel:[0,1,0]
	v_pk_fma_f32 v[134:135], v[186:187], v[52:53], v[134:135] op_sel:[0,1,0]
	v_pk_fma_f32 v[136:137], v[184:185], v[84:85], v[136:137] op_sel:[0,1,0]
	v_pk_fma_f32 v[138:139], v[186:187], v[84:85], v[138:139] op_sel:[0,1,0]
	v_pk_fma_f32 v[140:141], v[184:185], v[116:117], v[140:141] op_sel:[0,1,0]
	v_pk_fma_f32 v[142:143], v[186:187], v[116:117], v[142:143] op_sel:[0,1,0]
	s_waitcnt vmcnt(9)
	v_pk_fma_f32 v[128:129], v[188:189], v[22:23], v[128:129] op_sel_hi:[1,0,1]
	v_pk_fma_f32 v[130:131], v[190:191], v[22:23], v[130:131] op_sel_hi:[1,0,1]
	v_pk_fma_f32 v[132:133], v[188:189], v[54:55], v[132:133] op_sel_hi:[1,0,1]
	v_pk_fma_f32 v[134:135], v[190:191], v[54:55], v[134:135] op_sel_hi:[1,0,1]
	v_pk_fma_f32 v[136:137], v[188:189], v[86:87], v[136:137] op_sel_hi:[1,0,1]
	v_pk_fma_f32 v[138:139], v[190:191], v[86:87], v[138:139] op_sel_hi:[1,0,1]
	v_pk_fma_f32 v[140:141], v[188:189], v[118:119], v[140:141] op_sel_hi:[1,0,1]
	v_pk_fma_f32 v[142:143], v[190:191], v[118:119], v[142:143] op_sel_hi:[1,0,1]
	s_waitcnt vmcnt(8)
	v_pk_fma_f32 v[128:129], v[192:193], v[22:23], v[128:129] op_sel:[0,1,0]
	v_pk_fma_f32 v[130:131], v[194:195], v[22:23], v[130:131] op_sel:[0,1,0]
	v_pk_fma_f32 v[132:133], v[192:193], v[54:55], v[132:133] op_sel:[0,1,0]
	v_pk_fma_f32 v[134:135], v[194:195], v[54:55], v[134:135] op_sel:[0,1,0]
	v_pk_fma_f32 v[136:137], v[192:193], v[86:87], v[136:137] op_sel:[0,1,0]
	v_pk_fma_f32 v[138:139], v[194:195], v[86:87], v[138:139] op_sel:[0,1,0]
	v_pk_fma_f32 v[140:141], v[192:193], v[118:119], v[140:141] op_sel:[0,1,0]
	v_pk_fma_f32 v[142:143], v[194:195], v[118:119], v[142:143] op_sel:[0,1,0]
	s_waitcnt vmcnt(7)
	v_pk_fma_f32 v[128:129], v[196:197], v[24:25], v[128:129] op_sel_hi:[1,0,1]
	v_pk_fma_f32 v[130:131], v[198:199], v[24:25], v[130:131] op_sel_hi:[1,0,1]
	v_pk_fma_f32 v[132:133], v[196:197], v[56:57], v[132:133] op_sel_hi:[1,0,1]
	v_pk_fma_f32 v[134:135], v[198:199], v[56:57], v[134:135] op_sel_hi:[1,0,1]
	v_pk_fma_f32 v[136:137], v[196:197], v[88:89], v[136:137] op_sel_hi:[1,0,1]
	v_pk_fma_f32 v[138:139], v[198:199], v[88:89], v[138:139] op_sel_hi:[1,0,1]
	v_pk_fma_f32 v[140:141], v[196:197], v[120:121], v[140:141] op_sel_hi:[1,0,1]
	v_pk_fma_f32 v[142:143], v[198:199], v[120:121], v[142:143] op_sel_hi:[1,0,1]
	s_waitcnt vmcnt(6)
	v_pk_fma_f32 v[128:129], v[200:201], v[24:25], v[128:129] op_sel:[0,1,0]
	v_pk_fma_f32 v[130:131], v[202:203], v[24:25], v[130:131] op_sel:[0,1,0]
	v_pk_fma_f32 v[132:133], v[200:201], v[56:57], v[132:133] op_sel:[0,1,0]
	v_pk_fma_f32 v[134:135], v[202:203], v[56:57], v[134:135] op_sel:[0,1,0]
	v_pk_fma_f32 v[136:137], v[200:201], v[88:89], v[136:137] op_sel:[0,1,0]
	v_pk_fma_f32 v[138:139], v[202:203], v[88:89], v[138:139] op_sel:[0,1,0]
	v_pk_fma_f32 v[140:141], v[200:201], v[120:121], v[140:141] op_sel:[0,1,0]
	v_pk_fma_f32 v[142:143], v[202:203], v[120:121], v[142:143] op_sel:[0,1,0]
	s_waitcnt vmcnt(5)
	v_pk_fma_f32 v[128:129], v[204:205], v[26:27], v[128:129] op_sel_hi:[1,0,1]
	v_pk_fma_f32 v[130:131], v[206:207], v[26:27], v[130:131] op_sel_hi:[1,0,1]
	v_pk_fma_f32 v[132:133], v[204:205], v[58:59], v[132:133] op_sel_hi:[1,0,1]
	v_pk_fma_f32 v[134:135], v[206:207], v[58:59], v[134:135] op_sel_hi:[1,0,1]
	v_pk_fma_f32 v[136:137], v[204:205], v[90:91], v[136:137] op_sel_hi:[1,0,1]
	v_pk_fma_f32 v[138:139], v[206:207], v[90:91], v[138:139] op_sel_hi:[1,0,1]
	v_pk_fma_f32 v[140:141], v[204:205], v[122:123], v[140:141] op_sel_hi:[1,0,1]
	v_pk_fma_f32 v[142:143], v[206:207], v[122:123], v[142:143] op_sel_hi:[1,0,1]
	s_waitcnt vmcnt(4)
	v_pk_fma_f32 v[128:129], v[208:209], v[26:27], v[128:129] op_sel:[0,1,0]
	v_pk_fma_f32 v[130:131], v[210:211], v[26:27], v[130:131] op_sel:[0,1,0]
	v_pk_fma_f32 v[132:133], v[208:209], v[58:59], v[132:133] op_sel:[0,1,0]
	v_pk_fma_f32 v[134:135], v[210:211], v[58:59], v[134:135] op_sel:[0,1,0]
	v_pk_fma_f32 v[136:137], v[208:209], v[90:91], v[136:137] op_sel:[0,1,0]
	v_pk_fma_f32 v[138:139], v[210:211], v[90:91], v[138:139] op_sel:[0,1,0]
	v_pk_fma_f32 v[140:141], v[208:209], v[122:123], v[140:141] op_sel:[0,1,0]
	v_pk_fma_f32 v[142:143], v[210:211], v[122:123], v[142:143] op_sel:[0,1,0]
	s_waitcnt vmcnt(3)
	v_pk_fma_f32 v[128:129], v[212:213], v[28:29], v[128:129] op_sel_hi:[1,0,1]
	v_pk_fma_f32 v[130:131], v[214:215], v[28:29], v[130:131] op_sel_hi:[1,0,1]
	v_pk_fma_f32 v[132:133], v[212:213], v[60:61], v[132:133] op_sel_hi:[1,0,1]
	v_pk_fma_f32 v[134:135], v[214:215], v[60:61], v[134:135] op_sel_hi:[1,0,1]
	v_pk_fma_f32 v[136:137], v[212:213], v[92:93], v[136:137] op_sel_hi:[1,0,1]
	v_pk_fma_f32 v[138:139], v[214:215], v[92:93], v[138:139] op_sel_hi:[1,0,1]
	v_pk_fma_f32 v[140:141], v[212:213], v[124:125], v[140:141] op_sel_hi:[1,0,1]
	v_pk_fma_f32 v[142:143], v[214:215], v[124:125], v[142:143] op_sel_hi:[1,0,1]
	s_waitcnt vmcnt(2)
	v_pk_fma_f32 v[128:129], v[216:217], v[28:29], v[128:129] op_sel:[0,1,0]
	v_pk_fma_f32 v[130:131], v[218:219], v[28:29], v[130:131] op_sel:[0,1,0]
	v_pk_fma_f32 v[132:133], v[216:217], v[60:61], v[132:133] op_sel:[0,1,0]
	v_pk_fma_f32 v[134:135], v[218:219], v[60:61], v[134:135] op_sel:[0,1,0]
	v_pk_fma_f32 v[136:137], v[216:217], v[92:93], v[136:137] op_sel:[0,1,0]
	v_pk_fma_f32 v[138:139], v[218:219], v[92:93], v[138:139] op_sel:[0,1,0]
	v_pk_fma_f32 v[140:141], v[216:217], v[124:125], v[140:141] op_sel:[0,1,0]
	v_pk_fma_f32 v[142:143], v[218:219], v[124:125], v[142:143] op_sel:[0,1,0]
	s_waitcnt vmcnt(1)
	v_pk_fma_f32 v[128:129], v[220:221], v[30:31], v[128:129] op_sel_hi:[1,0,1]
	v_pk_fma_f32 v[130:131], v[222:223], v[30:31], v[130:131] op_sel_hi:[1,0,1]
	v_pk_fma_f32 v[132:133], v[220:221], v[62:63], v[132:133] op_sel_hi:[1,0,1]
	v_pk_fma_f32 v[134:135], v[222:223], v[62:63], v[134:135] op_sel_hi:[1,0,1]
	v_pk_fma_f32 v[136:137], v[220:221], v[94:95], v[136:137] op_sel_hi:[1,0,1]
	v_pk_fma_f32 v[138:139], v[222:223], v[94:95], v[138:139] op_sel_hi:[1,0,1]
	v_pk_fma_f32 v[140:141], v[220:221], v[126:127], v[140:141] op_sel_hi:[1,0,1]
	v_pk_fma_f32 v[142:143], v[222:223], v[126:127], v[142:143] op_sel_hi:[1,0,1]
	s_waitcnt vmcnt(0)
	v_pk_fma_f32 v[128:129], v[224:225], v[30:31], v[128:129] op_sel:[0,1,0]
	v_pk_fma_f32 v[130:131], v[226:227], v[30:31], v[130:131] op_sel:[0,1,0]
	v_pk_fma_f32 v[132:133], v[224:225], v[62:63], v[132:133] op_sel:[0,1,0]
	v_pk_fma_f32 v[134:135], v[226:227], v[62:63], v[134:135] op_sel:[0,1,0]
	v_pk_fma_f32 v[136:137], v[224:225], v[94:95], v[136:137] op_sel:[0,1,0]
	v_pk_fma_f32 v[138:139], v[226:227], v[94:95], v[138:139] op_sel:[0,1,0]
	v_pk_fma_f32 v[140:141], v[224:225], v[126:127], v[140:141] op_sel:[0,1,0]
	v_pk_fma_f32 v[142:143], v[226:227], v[126:127], v[142:143] op_sel:[0,1,0]
	global_store_dwordx4 v145, v[128:131], s[24:25]
	s_add_u32 s24, s24, s27
	s_addc_u32 s25, s25, 0
	global_store_dwordx4 v145, v[132:135], s[24:25]
	s_add_u32 s24, s24, s27
	s_addc_u32 s25, s25, 0
	global_store_dwordx4 v145, v[136:139], s[24:25]
	s_add_u32 s24, s24, s27
	s_addc_u32 s25, s25, 0
	global_store_dwordx4 v145, v[140:143], s[24:25]
	s_add_u32 s12, s12, s13
	s_cmp_lt_u32 s12, 0x580
	s_cbranch_scc1 .Lshw_item
